# RWKV helper: rsqrt denormal scaling and exp2 underflow handling that cannot trigger removed (bit-identical), 52 fewer VALU per chunk
# speedup vs baseline: 1.0013x; 1.0013x over previous
.LBB0_398:
	s_or_b64 exec, exec, s[38:39]
	v_lshl_or_b32 v2, s8, 10, v142
	v_mov_b32_e32 v3, v0
	v_lshl_add_u64 v[2:3], v[68:69], 0, v[2:3]
	global_load_ushort v212, v[2:3], off
	global_load_ushort v213, v[2:3], off offset:1024
	global_load_ushort v214, v[2:3], off offset:2048
	global_load_ushort v215, v[2:3], off offset:3072
	v_add_u32_e32 v91, v143, v102
	ds_read_b128 v[92:95], v91 offset:12544
	ds_read_b128 v[164:167], v91 offset:13056
	ds_read_b128 v[216:219], v91 offset:13568
	ds_read_b128 v[220:223], v146 offset:12544
	ds_read_b128 v[224:227], v91 offset:14592
	ds_read_b128 v[228:231], v91 offset:15104
	ds_read_b128 v[244:247], v91 offset:15616
	ds_read_b128 v[248:251], v147 offset:12544
	v_add_u32_e32 v96, 0xf000, v138
	v_add_u32_e32 v97, 0xf400, v138
	v_add_u32_e32 v159, 0xf800, v138
	s_andn2_b64 vcc, exec, s[50:51]
	s_waitcnt lgkmcnt(7)
	v_mfma_f32_16x16x32_bf16 v[92:95], v[12:15], v[92:95], 0
	s_waitcnt lgkmcnt(6)
	v_mfma_f32_16x16x32_bf16 v[164:167], v[12:15], v[164:167], 0
	s_waitcnt lgkmcnt(5)
	v_mfma_f32_16x16x32_bf16 v[216:219], v[12:15], v[216:219], 0
	s_waitcnt lgkmcnt(4)
	v_mfma_f32_16x16x32_bf16 v[220:223], v[12:15], v[220:223], 0
	s_waitcnt lgkmcnt(3)
	v_mfma_f32_16x16x32_bf16 v[224:227], v[12:15], v[224:227], 0
	s_waitcnt lgkmcnt(2)
	v_mfma_f32_16x16x32_bf16 v[228:231], v[12:15], v[228:231], 0
	s_waitcnt lgkmcnt(1)
	v_mfma_f32_16x16x32_bf16 v[244:247], v[12:15], v[244:247], 0
	s_waitcnt lgkmcnt(0)
	v_mfma_f32_16x16x32_bf16 v[248:251], v[12:15], v[248:251], 0
	ds_write2_b32 v96, v92, v164 offset0:192 offset1:208
	ds_write2_b32 v97, v93, v165 offset0:64 offset1:80
	ds_write2_b32 v97, v94, v166 offset0:192 offset1:208
	ds_write2_b32 v159, v95, v167 offset0:64 offset1:80
	ds_write2_b32 v96, v216, v220 offset0:224 offset1:240
	ds_write2_b32 v97, v217, v221 offset0:96 offset1:112
	ds_write2_b32 v97, v218, v222 offset0:224 offset1:240
	ds_write2_b32 v159, v219, v223 offset0:96 offset1:112
	ds_write2_b32 v97, v224, v228 offset1:16
	ds_write2_b32 v97, v225, v229 offset0:128 offset1:144
	ds_write2_b32 v159, v226, v230 offset1:16
	ds_write2_b32 v159, v227, v231 offset0:128 offset1:144
	ds_write2_b32 v97, v244, v248 offset0:32 offset1:48
	ds_write2_b32 v97, v245, v249 offset0:160 offset1:176
	ds_write2_b32 v159, v246, v250 offset0:32 offset1:48
	ds_write2_b32 v159, v247, v251 offset0:160 offset1:176
	s_waitcnt lgkmcnt(0)
	ds_read2st64_b32 v[216:217], v140 offset1:1
	ds_read2st64_b32 v[218:219], v140 offset0:2 offset1:3
	ds_read2st64_b32 v[220:221], v140 offset0:4 offset1:5
	ds_read2st64_b32 v[222:223], v140 offset0:6 offset1:7
	ds_read2st64_b32 v[224:225], v140 offset0:8 offset1:9
	ds_read2st64_b32 v[226:227], v140 offset0:10 offset1:11
	ds_read2st64_b32 v[228:229], v140 offset0:12 offset1:13
	ds_read2st64_b32 v[230:231], v140 offset0:14 offset1:15
	ds_read2st64_b32 v[244:245], v140 offset0:16 offset1:17
	ds_read2st64_b32 v[246:247], v140 offset0:18 offset1:19
	ds_read2st64_b32 v[248:249], v140 offset0:20 offset1:21
	ds_read2st64_b32 v[250:251], v140 offset0:22 offset1:23
	ds_read2st64_b32 v[92:93], v140 offset0:24 offset1:25
	ds_read2st64_b32 v[94:95], v140 offset0:26 offset1:27
	ds_read2st64_b32 v[164:165], v140 offset0:28 offset1:29
	ds_read2st64_b32 v[166:167], v140 offset0:30 offset1:31
	s_waitcnt lgkmcnt(15)
	v_pk_fma_f32 v[14:15], v[64:65], v[60:61], v[216:217] op_sel:[0,1,0] op_sel_hi:[0,0,1] neg_lo:[1,0,0]
	v_pk_fma_f32 v[60:61], v[56:57], v[60:61], v[14:15] op_sel_hi:[0,1,1]
	v_cvt_pk_bf16_f32 v12, v60, v61
	ds_write_b16 v141, v12 offset:8192
	ds_write_b16_d16_hi v141, v12 offset:8320
	s_waitcnt lgkmcnt(15)
	v_pk_fma_f32 v[14:15], v[64:65], v[60:61], v[218:219] op_sel:[0,1,0] op_sel_hi:[0,0,1] neg_lo:[1,0,0]
	v_pk_fma_f32 v[60:61], v[56:57], v[60:61], v[14:15] op_sel_hi:[0,1,1]
	v_cvt_pk_bf16_f32 v13, v60, v61
	ds_write_b16 v141, v13 offset:8464
	ds_write_b16_d16_hi v141, v13 offset:8592
	s_waitcnt lgkmcnt(15)
	v_pk_fma_f32 v[14:15], v[64:65], v[60:61], v[220:221] op_sel:[0,1,0] op_sel_hi:[0,0,1] neg_lo:[1,0,0]
	v_pk_fma_f32 v[60:61], v[56:57], v[60:61], v[14:15] op_sel_hi:[0,1,1]
	v_cvt_pk_bf16_f32 v12, v60, v61
	ds_write_b16 v141, v12 offset:8736
	ds_write_b16_d16_hi v141, v12 offset:8864
	s_waitcnt lgkmcnt(15)
	v_pk_fma_f32 v[14:15], v[64:65], v[60:61], v[222:223] op_sel:[0,1,0] op_sel_hi:[0,0,1] neg_lo:[1,0,0]
	v_pk_fma_f32 v[60:61], v[56:57], v[60:61], v[14:15] op_sel_hi:[0,1,1]
	v_cvt_pk_bf16_f32 v13, v60, v61
	ds_write_b16 v141, v13 offset:9008
	ds_write_b16_d16_hi v141, v13 offset:9136
	s_waitcnt lgkmcnt(15)
	v_pk_fma_f32 v[14:15], v[64:65], v[60:61], v[224:225] op_sel:[0,1,0] op_sel_hi:[0,0,1] neg_lo:[1,0,0]
	v_pk_fma_f32 v[60:61], v[56:57], v[60:61], v[14:15] op_sel_hi:[0,1,1]
	v_cvt_pk_bf16_f32 v12, v60, v61
	ds_write_b16 v141, v12 offset:9280
	ds_write_b16_d16_hi v141, v12 offset:9408
	s_waitcnt lgkmcnt(15)
	v_pk_fma_f32 v[14:15], v[64:65], v[60:61], v[226:227] op_sel:[0,1,0] op_sel_hi:[0,0,1] neg_lo:[1,0,0]
	v_pk_fma_f32 v[60:61], v[56:57], v[60:61], v[14:15] op_sel_hi:[0,1,1]
	v_cvt_pk_bf16_f32 v13, v60, v61
	ds_write_b16 v141, v13 offset:9552
	ds_write_b16_d16_hi v141, v13 offset:9680
	s_waitcnt lgkmcnt(15)
	v_pk_fma_f32 v[14:15], v[64:65], v[60:61], v[228:229] op_sel:[0,1,0] op_sel_hi:[0,0,1] neg_lo:[1,0,0]
	v_pk_fma_f32 v[60:61], v[56:57], v[60:61], v[14:15] op_sel_hi:[0,1,1]
	v_cvt_pk_bf16_f32 v12, v60, v61
	ds_write_b16 v141, v12 offset:9824
	ds_write_b16_d16_hi v141, v12 offset:9952
	s_waitcnt lgkmcnt(15)
	v_pk_fma_f32 v[14:15], v[64:65], v[60:61], v[230:231] op_sel:[0,1,0] op_sel_hi:[0,0,1] neg_lo:[1,0,0]
	v_pk_fma_f32 v[60:61], v[56:57], v[60:61], v[14:15] op_sel_hi:[0,1,1]
	v_cvt_pk_bf16_f32 v13, v60, v61
	ds_write_b16 v141, v13 offset:10096
	ds_write_b16_d16_hi v141, v13 offset:10224
	s_waitcnt lgkmcnt(15)
	v_pk_fma_f32 v[14:15], v[64:65], v[60:61], v[244:245] op_sel:[0,1,0] op_sel_hi:[0,0,1] neg_lo:[1,0,0]
	v_pk_fma_f32 v[60:61], v[56:57], v[60:61], v[14:15] op_sel_hi:[0,1,1]
	v_cvt_pk_bf16_f32 v12, v60, v61
	ds_write_b16 v141, v12 offset:10368
	ds_write_b16_d16_hi v141, v12 offset:10496
	s_waitcnt lgkmcnt(15)
	v_pk_fma_f32 v[14:15], v[64:65], v[60:61], v[246:247] op_sel:[0,1,0] op_sel_hi:[0,0,1] neg_lo:[1,0,0]
	v_pk_fma_f32 v[60:61], v[56:57], v[60:61], v[14:15] op_sel_hi:[0,1,1]
	v_cvt_pk_bf16_f32 v13, v60, v61
	ds_write_b16 v141, v13 offset:10640
	ds_write_b16_d16_hi v141, v13 offset:10768
	s_waitcnt lgkmcnt(15)
	v_pk_fma_f32 v[14:15], v[64:65], v[60:61], v[248:249] op_sel:[0,1,0] op_sel_hi:[0,0,1] neg_lo:[1,0,0]
	v_pk_fma_f32 v[60:61], v[56:57], v[60:61], v[14:15] op_sel_hi:[0,1,1]
	v_cvt_pk_bf16_f32 v12, v60, v61
	ds_write_b16 v141, v12 offset:10912
	ds_write_b16_d16_hi v141, v12 offset:11040
	s_waitcnt lgkmcnt(15)
	v_pk_fma_f32 v[14:15], v[64:65], v[60:61], v[250:251] op_sel:[0,1,0] op_sel_hi:[0,0,1] neg_lo:[1,0,0]
	v_pk_fma_f32 v[60:61], v[56:57], v[60:61], v[14:15] op_sel_hi:[0,1,1]
	v_cvt_pk_bf16_f32 v13, v60, v61
	ds_write_b16 v141, v13 offset:11184
	ds_write_b16_d16_hi v141, v13 offset:11312
	s_waitcnt lgkmcnt(15)
	v_pk_fma_f32 v[14:15], v[64:65], v[60:61], v[92:93] op_sel:[0,1,0] op_sel_hi:[0,0,1] neg_lo:[1,0,0]
	v_pk_fma_f32 v[60:61], v[56:57], v[60:61], v[14:15] op_sel_hi:[0,1,1]
	v_cvt_pk_bf16_f32 v12, v60, v61
	ds_write_b16 v141, v12 offset:11456
	ds_write_b16_d16_hi v141, v12 offset:11584
	s_waitcnt lgkmcnt(15)
	v_pk_fma_f32 v[14:15], v[64:65], v[60:61], v[94:95] op_sel:[0,1,0] op_sel_hi:[0,0,1] neg_lo:[1,0,0]
	v_pk_fma_f32 v[60:61], v[56:57], v[60:61], v[14:15] op_sel_hi:[0,1,1]
	v_cvt_pk_bf16_f32 v13, v60, v61
	ds_write_b16 v141, v13 offset:11728
	ds_write_b16_d16_hi v141, v13 offset:11856
	s_waitcnt lgkmcnt(15)
	v_pk_fma_f32 v[14:15], v[64:65], v[60:61], v[164:165] op_sel:[0,1,0] op_sel_hi:[0,0,1] neg_lo:[1,0,0]
	v_pk_fma_f32 v[60:61], v[56:57], v[60:61], v[14:15] op_sel_hi:[0,1,1]
	v_cvt_pk_bf16_f32 v12, v60, v61
	ds_write_b16 v141, v12 offset:12000
	ds_write_b16_d16_hi v141, v12 offset:12128
	s_waitcnt lgkmcnt(15)
	v_pk_fma_f32 v[14:15], v[64:65], v[60:61], v[166:167] op_sel:[0,1,0] op_sel_hi:[0,0,1] neg_lo:[1,0,0]
	v_pk_fma_f32 v[60:61], v[56:57], v[60:61], v[14:15] op_sel_hi:[0,1,1]
	v_cvt_pk_bf16_f32 v13, v60, v61
	ds_write_b16 v141, v13 offset:12272
	ds_write_b16_d16_hi v141, v13 offset:12400
	s_waitcnt lgkmcnt(0)
	ds_read_b128 v[12:15], v144 offset:8192
	ds_read_b128 v[92:95], v145 offset:16640
	ds_read_b128 v[216:219], v144 offset:8256
	ds_read_b128 v[220:223], v145 offset:16704
	ds_read_b128 v[224:227], v144 offset:8320
	ds_read_b128 v[228:231], v145 offset:16768
	ds_read_b128 v[244:247], v144 offset:8384
	ds_read_b128 v[248:251], v145 offset:16832
	s_waitcnt lgkmcnt(6)
	v_mfma_f32_16x16x32_bf16 v[12:15], v[12:15], v[92:95], 0
	s_waitcnt lgkmcnt(4)
	v_mfma_f32_16x16x32_bf16 v[12:15], v[216:219], v[220:223], v[12:15]
	s_waitcnt lgkmcnt(2)
	v_mfma_f32_16x16x32_bf16 v[12:15], v[224:227], v[228:231], v[12:15]
	s_waitcnt lgkmcnt(0)
	v_mfma_f32_16x16x32_bf16 v[12:15], v[244:247], v[248:251], v[12:15]
	s_nop 7
	s_waitcnt vmcnt(0)
	v_lshlrev_b32_e32 v88, 16, v212
	v_lshlrev_b32_e32 v89, 16, v213
	v_lshlrev_b32_e32 v90, 16, v214
	v_lshlrev_b32_e32 v91, 16, v215
	v_pk_fma_f32 v[12:13], v[148:149], v[88:89], v[12:13] op_sel_hi:[0,1,1]
	v_pk_fma_f32 v[14:15], v[148:149], v[90:91], v[14:15] op_sel_hi:[0,1,1]
	v_mov_b32_e32 v88, 0x3dd2d3e8
	v_mov_b32_e32 v90, 0x40135761
	v_pk_mul_f32 v[92:93], v[12:13], v[12:13]
	v_pk_mul_f32 v[94:95], v[14:15], v[14:15]
	v_pk_fma_f32 v[92:93], v[92:93], v[88:89], v[90:91] op_sel_hi:[1,0,0]
	v_pk_fma_f32 v[94:95], v[94:95], v[88:89], v[90:91] op_sel_hi:[1,0,0]
	v_pk_mul_f32 v[92:93], v[92:93], v[12:13]
	v_pk_mul_f32 v[94:95], v[94:95], v[14:15]
	v_mov_b32_e32 v88, 1.0
	v_exp_f32_e32 v92, v92
	v_exp_f32_e32 v93, v93
	v_exp_f32_e32 v94, v94
	v_exp_f32_e32 v95, v95
	s_nop 0
	v_pk_add_f32 v[92:93], v[92:93], v[88:89] op_sel_hi:[1,0]
	v_pk_add_f32 v[94:95], v[94:95], v[88:89] op_sel_hi:[1,0]
	v_rcp_f32_e32 v92, v92
	v_rcp_f32_e32 v93, v93
	v_rcp_f32_e32 v94, v94
	v_rcp_f32_e32 v95, v95
	s_nop 0
	v_pk_fma_f32 v[12:13], v[12:13], v[92:93], v[12:13] neg_lo:[1,0,0] neg_hi:[1,0,0]
	v_pk_fma_f32 v[14:15], v[14:15], v[94:95], v[14:15] neg_lo:[1,0,0] neg_hi:[1,0,0]
	v_cvt_pk_bf16_f32 v12, v12, v13
	v_cvt_pk_bf16_f32 v14, v14, v15
	global_store_short v[2:3], v12, off
	global_store_short_d16_hi v[2:3], v12, off offset:1024
	global_store_short v[2:3], v14, off offset:2048
	global_store_short_d16_hi v[2:3], v14, off offset:3072
	s_waitcnt lgkmcnt(0)
	v_lshlrev_b32_e32 v1, 2, v128
	s_cbranch_vccnz .LBB0_408
	s_waitcnt vmcnt(4)
	v_lshlrev_b32_e32 v16, 16, v176
	v_lshlrev_b32_e32 v30, 16, v177
	v_lshlrev_b32_e32 v32, 16, v178
	v_lshlrev_b32_e32 v36, 16, v179
	v_lshlrev_b32_e32 v17, 16, v180
	v_lshlrev_b32_e32 v26, 16, v181
	v_lshlrev_b32_e32 v27, 16, v182
	v_lshlrev_b32_e32 v28, 16, v183
	v_lshlrev_b32_e32 v29, 16, v184
	v_lshlrev_b32_e32 v31, 16, v185
	v_lshlrev_b32_e32 v33, 16, v186
	v_lshlrev_b32_e32 v37, 16, v187
	v_lshlrev_b32_e32 v34, 16, v188
	v_lshlrev_b32_e32 v35, 16, v189
	v_lshlrev_b32_e32 v38, 16, v190
	v_lshlrev_b32_e32 v39, 16, v195
	v_lshlrev_b32_e32 v40, 16, v197
	v_lshlrev_b32_e32 v43, 16, v198
	v_lshlrev_b32_e32 v42, 16, v199
	v_lshlrev_b32_e32 v45, 16, v200
	v_lshlrev_b32_e32 v44, 16, v201
	v_lshlrev_b32_e32 v46, 16, v203
	v_lshlrev_b32_e32 v49, 16, v204
	v_lshlrev_b32_e32 v48, 16, v205
	v_lshlrev_b32_e32 v41, 16, v196
	v_lshlrev_b32_e32 v47, 16, v202
	v_lshlrev_b32_e32 v51, 16, v206
	v_lshlrev_b32_e32 v50, 16, v207
	v_lshlrev_b32_e32 v53, 16, v191
	v_lshlrev_b32_e32 v52, 16, v193
	v_lshlrev_b32_e32 v55, 16, v192
	v_lshlrev_b32_e32 v54, 16, v194
	v_add_f32_e32 v88, v155, v35
	v_mul_f32_e32 v88, 0xbfb8aa3b, v88
	v_exp_f32_e32 v88, v88
	v_pk_add_f32 v[12:13], v[32:33], v[26:27] neg_lo:[0,1] neg_hi:[0,1]
	v_pk_add_f32 v[2:3], v[30:31], v[16:17] neg_lo:[0,1] neg_hi:[0,1]
	v_fma_f32 v13, v150, v13, v27
	v_add_f32_e32 v88, 1.0, v88
	v_rcp_f32_e32 v88, v88
	v_mul_f32_e32 v92, v157, v13
	v_fma_f32 v3, v149, v3, v17
	s_bitcmp1_b32 s3, 0
	v_mul_f32_e32 v89, 0xbf6002b1, v88
	s_nop 0
	s_cselect_b32 s8, 0x5000, 0
	v_mov_b32_e32 v94, v0
	s_nop 0
	s_nop 0
	v_exp_f32_e32 v88, v89
	s_nop 0
	s_add_i32 s9, s8, 0
	s_mul_i32 s8, s3, 0xab
	v_mov_b32_e32 v90, v88
	v_add_f32_e32 v88, v154, v39
	v_mul_f32_e32 v88, 0xbfb8aa3b, v88
	v_exp_f32_e32 v88, v88
	v_mov_b32_e32 v89, v0
	s_bfe_u32 s8, s8, 0x70009
	s_mul_i32 s8, s8, 3
	v_add_f32_e32 v88, 1.0, v88
	v_rcp_f32_e32 v91, v88
	v_mul_f32_e32 v88, v92, v92
	s_sub_i32 s8, s3, s8
	s_and_b32 s8, s8, 0xff
	v_mov_b32_dpp v89, v88 quad_perm:[1,0,3,2] row_mask:0xf bank_mask:0xf
	v_fmac_f32_e32 v89, v92, v92
	s_mulk_i32 s8, 0x1100
	s_add_i32 s8, s8, 0
	v_add_f32_dpp v88, v89, v89 quad_perm:[2,3,0,1] row_mask:0xf bank_mask:0xf bound_ctrl:1
	v_pk_add_f32 v[14:15], v[36:37], v[28:29] neg_lo:[0,1] neg_hi:[0,1]
	s_nop 0
	v_add_f32_dpp v88, v88, v88 row_half_mirror row_mask:0xf bank_mask:0xf bound_ctrl:1
	v_fma_f32 v15, v151, v15, v29
	s_nop 0
	v_add_f32_dpp v88, v88, v88 row_mirror row_mask:0xf bank_mask:0xf bound_ctrl:1
	s_nop 0
	s_nop 1
	v_add_f32_dpp v88, v88, v88 row_bcast:15 row_mask:0xa bank_mask:0xf
	s_nop 1
	v_add_f32_dpp v88, v88, v88 row_bcast:31 row_mask:0xc bank_mask:0xf
	s_nop 0
	v_readlane_b32 s26, v88, 63
	s_nop 1
	v_mov_b32_e32 v88, s26
	v_add_f32_e32 v88, 0x2b8cbccc, v88
	s_nop 0
	s_nop 0
	s_nop 0
	s_nop 0
	v_rsq_f32_e32 v88, v88
	s_nop 0
	s_nop 0
	s_nop 0
	v_add_f32_e32 v89, -1.0, v91
	v_fma_f32 v89, v158, v89, 1.0
	v_mul_f32_e32 v13, v89, v13
	v_mul_f32_e32 v89, v13, v3
	v_mul_f32_e32 v93, v156, v89
	v_mul_f32_e64 v88, v92, -v88
	s_nop 0
	v_mov_b32_dpp v94, v93 quad_perm:[1,0,3,2] row_mask:0xf bank_mask:0xf
	v_fmac_f32_e32 v94, v156, v89
	s_nop 1
	v_add_f32_dpp v89, v94, v94 quad_perm:[2,3,0,1] row_mask:0xf bank_mask:0xf bound_ctrl:1
	s_nop 1
	v_add_f32_dpp v89, v89, v89 row_half_mirror row_mask:0xf bank_mask:0xf bound_ctrl:1
	s_nop 1
	v_add_f32_dpp v89, v89, v89 row_mirror row_mask:0xf bank_mask:0xf bound_ctrl:1
	s_nop 0
	s_nop 1
	v_add_f32_dpp v89, v89, v89 row_bcast:15 row_mask:0xa bank_mask:0xf
	s_nop 1
	v_add_f32_dpp v89, v89, v89 row_bcast:31 row_mask:0xc bank_mask:0xf
	s_nop 0
	v_readlane_b32 s38, v89, 63
	v_add_u32_e32 v89, s9, v1
	ds_write2st64_b32 v89, v90, v88 offset1:16
	v_mul_f32_e64 v88, v91, -v88
	ds_write2st64_b32 v89, v88, v13 offset0:32 offset1:48
	ds_write_b32 v89, v3 offset:16384
	v_add_u32_e32 v3, s8, v1
	ds_write_b32 v3, v15 offset:40960
	s_and_saveexec_b64 s[50:51], s[44:45]
	s_cbranch_execz .LBB0_401
	s_lshl_b32 s24, s96, 2
	s_add_i32 s24, s8, s24
	v_mov_b32_e32 v13, s24
	v_mov_b32_e32 v3, s38
	ds_write_b32 v13, v3 offset:45056
.LBB0_401:
	s_or_b64 exec, exec, s[50:51]
	v_fma_f32 v13, v149, v2, v16
	v_add_f32_e32 v2, v155, v34
	v_mul_f32_e32 v2, 0xbfb8aa3b, v2
	v_exp_f32_e32 v2, v2
	v_fma_f32 v12, v150, v12, v26
	v_mul_f32_e32 v89, v157, v12
	v_mov_b32_e32 v91, v0
	v_add_f32_e32 v2, 1.0, v2
	v_rcp_f32_e32 v2, v2
	v_fma_f32 v14, v151, v14, v28
	v_mul_f32_e32 v3, 0xbf6002b1, v2
	s_nop 0
	s_nop 1
	s_nop 0
	s_nop 0
	v_exp_f32_e32 v2, v3
	s_nop 0
	v_mov_b32_e32 v15, v2
	v_add_f32_e32 v2, v154, v38
	v_mul_f32_e32 v2, 0xbfb8aa3b, v2
	v_exp_f32_e32 v2, v2
	v_mov_b32_e32 v3, v0
	v_add_f32_e32 v2, 1.0, v2
	v_rcp_f32_e32 v88, v2
	v_mul_f32_e32 v2, v89, v89
	s_nop 1
	v_mov_b32_dpp v3, v2 quad_perm:[1,0,3,2] row_mask:0xf bank_mask:0xf
	v_fmac_f32_e32 v3, v89, v89
	s_nop 1
	v_add_f32_dpp v2, v3, v3 quad_perm:[2,3,0,1] row_mask:0xf bank_mask:0xf bound_ctrl:1
	s_nop 1
	v_add_f32_dpp v2, v2, v2 row_half_mirror row_mask:0xf bank_mask:0xf bound_ctrl:1
	s_nop 1
	v_add_f32_dpp v2, v2, v2 row_mirror row_mask:0xf bank_mask:0xf bound_ctrl:1
	s_nop 0
	s_nop 1
	v_add_f32_dpp v2, v2, v2 row_bcast:15 row_mask:0xa bank_mask:0xf
	s_nop 1
	v_add_f32_dpp v2, v2, v2 row_bcast:31 row_mask:0xc bank_mask:0xf
	s_nop 0
	v_readlane_b32 s26, v2, 63
	s_nop 1
	v_mov_b32_e32 v2, s26
	v_add_f32_e32 v2, 0x2b8cbccc, v2
	s_nop 0
	s_nop 0
	s_nop 0
	s_nop 0
	v_rsq_f32_e32 v2, v2
	s_nop 0
	s_nop 0
	s_nop 0
	v_add_f32_e32 v3, -1.0, v88
	v_fma_f32 v3, v158, v3, 1.0
	v_mul_f32_e32 v3, v3, v12
	v_mul_f32_e32 v12, v3, v13
	v_mul_f32_e32 v90, v156, v12
	v_mul_f32_e64 v2, v89, -v2
	s_nop 0
	v_mov_b32_dpp v91, v90 quad_perm:[1,0,3,2] row_mask:0xf bank_mask:0xf
	v_fmac_f32_e32 v91, v156, v12
	s_nop 1
	v_add_f32_dpp v12, v91, v91 quad_perm:[2,3,0,1] row_mask:0xf bank_mask:0xf bound_ctrl:1
	s_nop 1
	v_add_f32_dpp v12, v12, v12 row_half_mirror row_mask:0xf bank_mask:0xf bound_ctrl:1
	s_nop 1
	v_add_f32_dpp v12, v12, v12 row_mirror row_mask:0xf bank_mask:0xf bound_ctrl:1
	s_nop 0
	s_nop 1
	v_add_f32_dpp v12, v12, v12 row_bcast:15 row_mask:0xa bank_mask:0xf
	s_nop 1
	v_add_f32_dpp v12, v12, v12 row_bcast:31 row_mask:0xc bank_mask:0xf
	s_nop 0
	v_readlane_b32 s38, v12, 63
	v_lshlrev_b32_e32 v12, 2, v130
	v_add_u32_e32 v90, s9, v12
	ds_write2st64_b32 v90, v15, v2 offset1:16
	v_mul_f32_e64 v2, v88, -v2
	ds_write2st64_b32 v90, v2, v3 offset0:32 offset1:48
	ds_write_b32 v90, v13 offset:16384
	v_add_u32_e32 v2, s8, v12
	ds_write_b32 v2, v14 offset:40960
	s_and_saveexec_b64 s[50:51], s[44:45]
	s_cbranch_execz .LBB0_403
	s_lshl_b32 s24, s96, 2
	s_add_i32 s24, s8, s24
	s_nop 0
	v_mov_b32_e32 v2, s38
	v_mov_b32_e32 v3, s24
	ds_write_b32 v3, v2 offset:45072
.LBB0_403:
	s_or_b64 exec, exec, s[50:51]
	v_add_f32_e32 v88, v155, v53
	v_mul_f32_e32 v88, 0xbfb8aa3b, v88
	v_exp_f32_e32 v88, v88
	v_pk_add_f32 v[12:13], v[48:49], v[42:43] neg_lo:[0,1] neg_hi:[0,1]
	v_pk_add_f32 v[2:3], v[46:47], v[40:41] neg_lo:[0,1] neg_hi:[0,1]
	v_fma_f32 v13, v150, v13, v43
	v_add_f32_e32 v88, 1.0, v88
	v_rcp_f32_e32 v88, v88
	v_mul_f32_e32 v92, v157, v13
	v_fma_f32 v3, v149, v3, v41
	v_mov_b32_e32 v94, v0
	v_mul_f32_e32 v89, 0xbf6002b1, v88
	s_nop 0
	v_pk_add_f32 v[14:15], v[50:51], v[44:45] neg_lo:[0,1] neg_hi:[0,1]
	s_nop 0
	s_nop 0
	s_nop 0
	v_exp_f32_e32 v88, v89
	s_nop 0
	v_fma_f32 v15, v151, v15, v45
	v_mov_b32_e32 v90, v88
	v_add_f32_e32 v88, v154, v55
	v_mul_f32_e32 v88, 0xbfb8aa3b, v88
	v_exp_f32_e32 v88, v88
	v_mov_b32_e32 v89, v0
	v_add_f32_e32 v88, 1.0, v88
	v_rcp_f32_e32 v91, v88
	v_mul_f32_e32 v88, v92, v92
	s_nop 1
	v_mov_b32_dpp v89, v88 quad_perm:[1,0,3,2] row_mask:0xf bank_mask:0xf
	v_fmac_f32_e32 v89, v92, v92
	s_nop 1
	v_add_f32_dpp v88, v89, v89 quad_perm:[2,3,0,1] row_mask:0xf bank_mask:0xf bound_ctrl:1
	s_nop 1
	v_add_f32_dpp v88, v88, v88 row_half_mirror row_mask:0xf bank_mask:0xf bound_ctrl:1
	s_nop 1
	v_add_f32_dpp v88, v88, v88 row_mirror row_mask:0xf bank_mask:0xf bound_ctrl:1
	s_nop 0
	s_nop 1
	v_add_f32_dpp v88, v88, v88 row_bcast:15 row_mask:0xa bank_mask:0xf
	s_nop 1
	v_add_f32_dpp v88, v88, v88 row_bcast:31 row_mask:0xc bank_mask:0xf
	s_nop 0
	v_readlane_b32 s26, v88, 63
	s_nop 1
	v_mov_b32_e32 v88, s26
	v_add_f32_e32 v88, 0x2b8cbccc, v88
	s_nop 0
	s_nop 0
	s_nop 0
	s_nop 0
	v_rsq_f32_e32 v88, v88
	s_nop 0
	s_nop 0
	s_nop 0
	v_add_f32_e32 v89, -1.0, v91
	v_fma_f32 v89, v158, v89, 1.0
	v_mul_f32_e32 v13, v89, v13
	v_mul_f32_e32 v89, v13, v3
	v_mul_f32_e32 v93, v156, v89
	v_mul_f32_e64 v88, v92, -v88
	s_nop 0
	v_mov_b32_dpp v94, v93 quad_perm:[1,0,3,2] row_mask:0xf bank_mask:0xf
	v_fmac_f32_e32 v94, v156, v89
	s_nop 1
	v_add_f32_dpp v89, v94, v94 quad_perm:[2,3,0,1] row_mask:0xf bank_mask:0xf bound_ctrl:1
	s_nop 1
	v_add_f32_dpp v89, v89, v89 row_half_mirror row_mask:0xf bank_mask:0xf bound_ctrl:1
	s_nop 1
	v_add_f32_dpp v89, v89, v89 row_mirror row_mask:0xf bank_mask:0xf bound_ctrl:1
	s_nop 0
	s_nop 1
	v_add_f32_dpp v89, v89, v89 row_bcast:15 row_mask:0xa bank_mask:0xf
	s_nop 1
	v_add_f32_dpp v89, v89, v89 row_bcast:31 row_mask:0xc bank_mask:0xf
	s_nop 0
	v_readlane_b32 s38, v89, 63
	v_lshlrev_b32_e32 v89, 2, v132
	v_add_u32_e32 v93, s9, v89
	ds_write2st64_b32 v93, v90, v88 offset1:16
	v_mul_f32_e64 v88, v91, -v88
	ds_write2st64_b32 v93, v88, v13 offset0:32 offset1:48
	ds_write_b32 v93, v3 offset:16384
	v_add_u32_e32 v3, s8, v89
	ds_write_b32 v3, v15 offset:40960
	s_and_saveexec_b64 s[50:51], s[44:45]
	s_cbranch_execz .LBB0_405
	s_lshl_b32 s24, s96, 2
	s_add_i32 s24, s8, s24
	v_mov_b32_e32 v13, s24
	v_mov_b32_e32 v3, s38
	ds_write_b32 v13, v3 offset:45088
.LBB0_405:
	s_or_b64 exec, exec, s[50:51]
	v_fma_f32 v13, v149, v2, v40
	v_add_f32_e32 v2, v155, v52
	v_mul_f32_e32 v2, 0xbfb8aa3b, v2
	v_exp_f32_e32 v2, v2
	v_fma_f32 v12, v150, v12, v42
	v_mul_f32_e32 v89, v157, v12
	v_mov_b32_e32 v91, v0
	v_add_f32_e32 v2, 1.0, v2
	v_rcp_f32_e32 v2, v2
	v_fma_f32 v14, v151, v14, v44
	v_mul_f32_e32 v3, 0xbf6002b1, v2
	s_nop 0
	s_nop 1
	s_nop 0
	s_nop 0
	v_exp_f32_e32 v2, v3
	s_nop 0
	v_mov_b32_e32 v15, v2
	v_add_f32_e32 v2, v154, v54
	v_mul_f32_e32 v2, 0xbfb8aa3b, v2
	v_exp_f32_e32 v2, v2
	v_mov_b32_e32 v3, v0
	v_add_f32_e32 v2, 1.0, v2
	v_rcp_f32_e32 v88, v2
	v_mul_f32_e32 v2, v89, v89
	s_nop 1
	v_mov_b32_dpp v3, v2 quad_perm:[1,0,3,2] row_mask:0xf bank_mask:0xf
	v_fmac_f32_e32 v3, v89, v89
	s_nop 1
	v_add_f32_dpp v2, v3, v3 quad_perm:[2,3,0,1] row_mask:0xf bank_mask:0xf bound_ctrl:1
	s_nop 1
	v_add_f32_dpp v2, v2, v2 row_half_mirror row_mask:0xf bank_mask:0xf bound_ctrl:1
	s_nop 1
	v_add_f32_dpp v2, v2, v2 row_mirror row_mask:0xf bank_mask:0xf bound_ctrl:1
	s_nop 0
	s_nop 1
	v_add_f32_dpp v2, v2, v2 row_bcast:15 row_mask:0xa bank_mask:0xf
	s_nop 1
	v_add_f32_dpp v2, v2, v2 row_bcast:31 row_mask:0xc bank_mask:0xf
	s_nop 0
	v_readlane_b32 s26, v2, 63
	s_nop 1
	v_mov_b32_e32 v2, s26
	v_add_f32_e32 v2, 0x2b8cbccc, v2
	s_nop 0
	s_nop 0
	s_nop 0
	s_nop 0
	v_rsq_f32_e32 v2, v2
	s_nop 0
	s_nop 0
	s_nop 0
	v_add_f32_e32 v3, -1.0, v88
	v_fma_f32 v3, v158, v3, 1.0
	v_mul_f32_e32 v3, v3, v12
	v_mul_f32_e32 v12, v3, v13
	v_mul_f32_e32 v90, v156, v12
	v_mul_f32_e64 v2, v89, -v2
	s_nop 0
	v_mov_b32_dpp v91, v90 quad_perm:[1,0,3,2] row_mask:0xf bank_mask:0xf
	v_fmac_f32_e32 v91, v156, v12
	s_nop 1
	v_add_f32_dpp v12, v91, v91 quad_perm:[2,3,0,1] row_mask:0xf bank_mask:0xf bound_ctrl:1
	s_nop 1
	v_add_f32_dpp v12, v12, v12 row_half_mirror row_mask:0xf bank_mask:0xf bound_ctrl:1
	s_nop 1
	v_add_f32_dpp v12, v12, v12 row_mirror row_mask:0xf bank_mask:0xf bound_ctrl:1
	s_nop 0
	s_nop 1
	v_add_f32_dpp v12, v12, v12 row_bcast:15 row_mask:0xa bank_mask:0xf
	s_nop 1
	v_add_f32_dpp v12, v12, v12 row_bcast:31 row_mask:0xc bank_mask:0xf
	s_nop 0
	v_readlane_b32 s38, v12, 63
	v_lshlrev_b32_e32 v12, 2, v134
	v_add_u32_e32 v90, s9, v12
	ds_write2st64_b32 v90, v15, v2 offset1:16
	v_mul_f32_e64 v2, v88, -v2
	ds_write2st64_b32 v90, v2, v3 offset0:32 offset1:48
	ds_write_b32 v90, v13 offset:16384
	v_add_u32_e32 v2, s8, v12
	ds_write_b32 v2, v14 offset:40960
	s_and_saveexec_b64 s[50:51], s[44:45]
	s_cbranch_execz .LBB0_407
	s_lshl_b32 s9, s96, 2
	s_add_i32 s8, s8, s9
	s_nop 0
	v_mov_b32_e32 v2, s38
	v_mov_b32_e32 v3, s8
	ds_write_b32 v3, v2 offset:45104

.LBB0_408:
	s_andn2_b64 vcc, exec, s[36:37]
	s_mov_b32 s8, 1
	s_cbranch_vccnz .LBB0_410
	s_waitcnt vmcnt(4)
	v_lshlrev_b32_e32 v4, 16, v208
	v_lshlrev_b32_e32 v5, 16, v209
	v_lshlrev_b32_e32 v6, 16, v210
	v_lshlrev_b32_e32 v7, 16, v211
	s_add_i32 s8, s2, -1
	s_and_b32 s2, s8, 0xff
	s_mulk_i32 s2, 0xab
	s_lshr_b32 s2, s2, 9
	s_mul_i32 s2, s2, 3
	s_sub_i32 s2, s8, s2
	s_and_b32 s2, s2, 0xff
	s_lshl_b32 s9, s8, 12
	s_mulk_i32 s2, 0x1100
	s_and_b32 s9, s9, 0x1000
	s_add_i32 s2, s2, 0
	s_add_i32 s9, s9, 0
	v_lshlrev_b32_e32 v15, 2, v134
	v_add_u32_e32 v2, s9, v1
	v_add_u32_e32 v1, s2, v1
	v_lshlrev_b32_e32 v3, 2, v130
	v_lshlrev_b32_e32 v13, 2, v132
	v_add_u32_e32 v88, s9, v15
	v_add_u32_e32 v12, s9, v3
	v_add_u32_e32 v3, s2, v3
	v_add_u32_e32 v14, s9, v13
	v_add_u32_e32 v13, s2, v13
	v_add_u32_e32 v15, s2, v15
	ds_read_b32 v89, v2 offset:54016
	ds_read_b32 v1, v1 offset:40960
	ds_read_b32 v90, v12 offset:54016
	ds_read_b32 v91, v3 offset:40960
	ds_read_b32 v92, v14 offset:54016
	ds_read_b32 v93, v13 offset:40960
	ds_read_b32 v88, v88 offset:54016
	ds_read_b32 v94, v15 offset:40960
	s_waitcnt lgkmcnt(7)
	v_add_f32_dpp v2, v89, v89 quad_perm:[1,0,3,2] row_mask:0xf bank_mask:0xf bound_ctrl:1
	s_lshl_b32 s8, s8, 4
	s_add_u32 s36, s30, s8
	v_add_f32_dpp v2, v2, v2 quad_perm:[2,3,0,1] row_mask:0xf bank_mask:0xf bound_ctrl:1
	s_addc_u32 s37, s31, 0
	s_nop 0
	v_add_f32_dpp v2, v2, v2 row_half_mirror row_mask:0xf bank_mask:0xf bound_ctrl:1
	s_nop 1
	v_add_f32_dpp v2, v2, v2 row_mirror row_mask:0xf bank_mask:0xf bound_ctrl:1
	s_nop 0
	s_nop 1
	v_add_f32_dpp v2, v2, v2 row_bcast:15 row_mask:0xa bank_mask:0xf
	s_nop 1
	v_add_f32_dpp v2, v2, v2 row_bcast:31 row_mask:0xc bank_mask:0xf
	s_nop 0
	v_readlane_b32 s9, v2, 63
	s_nop 1
	v_mov_b32_e32 v2, s9
	v_fmac_f32_e32 v89, 0xbc800000, v2
	v_mul_f32_e32 v2, v89, v89
	v_mov_b32_e32 v3, v0
	s_nop 1
	v_mov_b32_dpp v3, v2 quad_perm:[1,0,3,2] row_mask:0xf bank_mask:0xf
	v_fmac_f32_e32 v3, v89, v89
	s_nop 1
	v_add_f32_dpp v2, v3, v3 quad_perm:[2,3,0,1] row_mask:0xf bank_mask:0xf bound_ctrl:1
	s_nop 1
	v_add_f32_dpp v2, v2, v2 row_half_mirror row_mask:0xf bank_mask:0xf bound_ctrl:1
	s_nop 1
	v_add_f32_dpp v2, v2, v2 row_mirror row_mask:0xf bank_mask:0xf bound_ctrl:1
	s_nop 0
	s_lshl_b32 s24, s96, 2
	s_nop 1
	v_add_f32_dpp v2, v2, v2 row_bcast:15 row_mask:0xa bank_mask:0xf
	s_nop 1
	v_add_f32_dpp v2, v2, v2 row_bcast:31 row_mask:0xc bank_mask:0xf
	s_nop 0
	v_readlane_b32 s9, v2, 63
	s_nop 1
	v_mov_b32_e32 v2, s9
	v_fmamk_f32 v2, v2, 0x3c800000, v233
	s_nop 0
	s_nop 0
	s_add_i32 s2, s2, s24
	s_or_b64 s[8:9], s[36:37], s[96:97]
	s_nop 0
	v_rsq_f32_e32 v12, v2
	v_mov_b32_e32 v2, s2
	v_add_u32_e32 v14, 0xb000, v2
	ds_read2_b32 v[2:3], v14 offset1:4
	s_nop 0
	s_nop 0
	v_mul_f32_e32 v12, v89, v12
	v_fma_f32 v15, v153, v12, v152
	s_waitcnt lgkmcnt(0)
	v_fmac_f32_e32 v15, v2, v1
	v_add_f32_dpp v2, v90, v90 quad_perm:[1,0,3,2] row_mask:0xf bank_mask:0xf bound_ctrl:1
	ds_read2_b32 v[12:13], v14 offset0:8 offset1:12
	v_mul_f32_e32 v1, v4, v15
	v_add_f32_dpp v2, v2, v2 quad_perm:[2,3,0,1] row_mask:0xf bank_mask:0xf bound_ctrl:1
	s_lshl_b64 s[8:9], s[8:9], 10
	v_cvt_pk_bf16_f32 v1, v1, v0
	s_nop 0
	v_add_f32_dpp v2, v2, v2 row_half_mirror row_mask:0xf bank_mask:0xf bound_ctrl:1
	s_nop 1
	v_add_f32_dpp v2, v2, v2 row_mirror row_mask:0xf bank_mask:0xf bound_ctrl:1
	s_nop 0
	s_nop 1
	v_add_f32_dpp v2, v2, v2 row_bcast:15 row_mask:0xa bank_mask:0xf
	s_nop 1
	v_add_f32_dpp v2, v2, v2 row_bcast:31 row_mask:0xc bank_mask:0xf
	s_nop 0
	v_readlane_b32 s2, v2, 63
	s_nop 1
	v_mov_b32_e32 v2, s2
	v_fmac_f32_e32 v90, 0xbc800000, v2
	v_mul_f32_e32 v2, v90, v90
	v_mov_b32_e32 v14, v0
	s_nop 1
	v_mov_b32_dpp v14, v2 quad_perm:[1,0,3,2] row_mask:0xf bank_mask:0xf
	v_fmac_f32_e32 v14, v90, v90
	s_nop 1
	v_add_f32_dpp v2, v14, v14 quad_perm:[2,3,0,1] row_mask:0xf bank_mask:0xf bound_ctrl:1
	s_nop 1
	v_add_f32_dpp v2, v2, v2 row_half_mirror row_mask:0xf bank_mask:0xf bound_ctrl:1
	s_nop 1
	v_add_f32_dpp v2, v2, v2 row_mirror row_mask:0xf bank_mask:0xf bound_ctrl:1
	s_nop 0
	s_nop 1
	v_add_f32_dpp v2, v2, v2 row_bcast:15 row_mask:0xa bank_mask:0xf
	s_nop 1
	v_add_f32_dpp v2, v2, v2 row_bcast:31 row_mask:0xc bank_mask:0xf
	s_nop 0
	v_readlane_b32 s2, v2, 63
	s_nop 1
	v_mov_b32_e32 v2, s2
	v_fmamk_f32 v2, v2, 0x3c800000, v233
	s_nop 0
	s_nop 0
	s_nop 1
	s_nop 0
	v_rsq_f32_e32 v2, v2
	v_lshl_add_u64 v[14:15], v[58:59], 0, s[8:9]
	global_store_short v[14:15], v1, off
	s_or_b64 s[8:9], s[36:37], s[12:13]
	s_nop 0
	v_mov_b32_e32 v1, v2
	v_add_f32_dpp v2, v92, v92 quad_perm:[1,0,3,2] row_mask:0xf bank_mask:0xf bound_ctrl:1
	v_mul_f32_e32 v1, v90, v1
	v_fma_f32 v1, v153, v1, v152
	v_add_f32_dpp v2, v2, v2 quad_perm:[2,3,0,1] row_mask:0xf bank_mask:0xf bound_ctrl:1
	v_fmac_f32_e32 v1, v3, v91
	s_lshl_b64 s[8:9], s[8:9], 10
	v_add_f32_dpp v2, v2, v2 row_half_mirror row_mask:0xf bank_mask:0xf bound_ctrl:1
	v_mul_f32_e32 v1, v5, v1
	v_cvt_pk_bf16_f32 v1, v1, v0
	s_nop 0
	v_add_f32_dpp v2, v2, v2 row_mirror row_mask:0xf bank_mask:0xf bound_ctrl:1
	s_nop 0
	s_nop 1
	v_add_f32_dpp v2, v2, v2 row_bcast:15 row_mask:0xa bank_mask:0xf
	s_nop 1
	v_add_f32_dpp v2, v2, v2 row_bcast:31 row_mask:0xc bank_mask:0xf
	s_nop 0
	v_readlane_b32 s2, v2, 63
	s_nop 1
	v_mov_b32_e32 v2, s2
	v_fmac_f32_e32 v92, 0xbc800000, v2
	v_mul_f32_e32 v2, v92, v92
	v_mov_b32_e32 v3, v0
	s_nop 1
	v_mov_b32_dpp v3, v2 quad_perm:[1,0,3,2] row_mask:0xf bank_mask:0xf
	v_fmac_f32_e32 v3, v92, v92
	s_nop 1
	v_add_f32_dpp v2, v3, v3 quad_perm:[2,3,0,1] row_mask:0xf bank_mask:0xf bound_ctrl:1
	s_nop 1
	v_add_f32_dpp v2, v2, v2 row_half_mirror row_mask:0xf bank_mask:0xf bound_ctrl:1
	s_nop 1
	v_add_f32_dpp v2, v2, v2 row_mirror row_mask:0xf bank_mask:0xf bound_ctrl:1
	s_nop 0
	s_nop 1
	v_add_f32_dpp v2, v2, v2 row_bcast:15 row_mask:0xa bank_mask:0xf
	s_nop 1
	v_add_f32_dpp v2, v2, v2 row_bcast:31 row_mask:0xc bank_mask:0xf
	s_nop 0
	v_readlane_b32 s2, v2, 63
	s_nop 1
	v_mov_b32_e32 v2, s2
	v_fmamk_f32 v2, v2, 0x3c800000, v233
	s_nop 0
	s_nop 0
	s_nop 1
	s_nop 0
	v_rsq_f32_e32 v14, v2
	v_lshl_add_u64 v[2:3], v[58:59], 0, s[8:9]
	global_store_short v[2:3], v1, off
	s_or_b64 s[8:9], s[36:37], s[14:15]
	v_add_f32_dpp v2, v88, v88 quad_perm:[1,0,3,2] row_mask:0xf bank_mask:0xf bound_ctrl:1
	s_nop 0
	v_mov_b32_e32 v1, v14
	v_add_f32_dpp v2, v2, v2 quad_perm:[2,3,0,1] row_mask:0xf bank_mask:0xf bound_ctrl:1
	v_mul_f32_e32 v1, v92, v1
	v_fma_f32 v1, v153, v1, v152
	v_add_f32_dpp v2, v2, v2 row_half_mirror row_mask:0xf bank_mask:0xf bound_ctrl:1
	s_waitcnt lgkmcnt(0)
	v_fmac_f32_e32 v1, v12, v93
	v_mul_f32_e32 v1, v6, v1
	v_add_f32_dpp v2, v2, v2 row_mirror row_mask:0xf bank_mask:0xf bound_ctrl:1
	s_lshl_b64 s[8:9], s[8:9], 10
	v_cvt_pk_bf16_f32 v1, v1, v0
	s_nop 1
	v_add_f32_dpp v2, v2, v2 row_bcast:15 row_mask:0xa bank_mask:0xf
	s_nop 1
	v_add_f32_dpp v2, v2, v2 row_bcast:31 row_mask:0xc bank_mask:0xf
	s_nop 0
	v_readlane_b32 s2, v2, 63
	s_nop 1
	v_mov_b32_e32 v2, s2
	v_fmac_f32_e32 v88, 0xbc800000, v2
	v_mul_f32_e32 v2, v88, v88
	v_mov_b32_e32 v3, v0
	s_nop 1
	v_mov_b32_dpp v3, v2 quad_perm:[1,0,3,2] row_mask:0xf bank_mask:0xf
	v_fmac_f32_e32 v3, v88, v88
	s_nop 1
	v_add_f32_dpp v2, v3, v3 quad_perm:[2,3,0,1] row_mask:0xf bank_mask:0xf bound_ctrl:1
	s_nop 1
	v_add_f32_dpp v2, v2, v2 row_half_mirror row_mask:0xf bank_mask:0xf bound_ctrl:1
	s_nop 1
	v_add_f32_dpp v2, v2, v2 row_mirror row_mask:0xf bank_mask:0xf bound_ctrl:1
	s_nop 0
	s_nop 1
	v_add_f32_dpp v2, v2, v2 row_bcast:15 row_mask:0xa bank_mask:0xf
	s_nop 1
	v_add_f32_dpp v2, v2, v2 row_bcast:31 row_mask:0xc bank_mask:0xf
	s_nop 0
	v_readlane_b32 s2, v2, 63
	s_nop 1
	v_mov_b32_e32 v2, s2
	v_fmamk_f32 v2, v2, 0x3c800000, v233
	s_nop 0
	s_nop 0
	s_nop 1
	s_nop 0
	v_rsq_f32_e32 v12, v2
	v_lshl_add_u64 v[2:3], v[58:59], 0, s[8:9]
	global_store_short v[2:3], v1, off
	s_or_b64 s[8:9], s[36:37], s[16:17]
	s_nop 0
	v_mov_b32_e32 v1, v12
	v_mul_f32_e32 v1, v88, v1
	v_fma_f32 v1, v153, v1, v152
	v_fmac_f32_e32 v1, v13, v94
	s_lshl_b64 s[8:9], s[8:9], 10
	v_mul_f32_e32 v1, v7, v1
	v_lshl_add_u64 v[2:3], v[58:59], 0, s[8:9]
	s_mov_b32 s8, s3
	v_cvt_pk_bf16_f32 v1, v1, v0
	global_store_short v[2:3], v1, off
